# P0 reorder: folded mixer weights (e) run first on waves 0-3 of every CU, weight transposes (d) rebalanced 12/6.5 items toward waves 4-7
# speedup vs baseline: 1.0280x; 1.0280x over previous
.LBB0_40:
	s_or_b64 exec, exec, s[14:15]
	s_lshl_b32 s4, s11, 14
	s_add_i32 s7, s4, 0
	s_mov_b32 s98, s0
	s_and_b32 s99, s0, 7
	s_cmp_lt_u32 s99, 4
	s_cbranch_scc0 .Lp0_d_entry
	s_lshr_b32 s100, s0, 3
	s_lshl_b32 s100, s100, 2
	s_add_i32 s0, s100, s99
	s_and_b32 s100, s0, 2
	s_lshl_b32 s100, s100, 7
	s_xor_b32 s0, s0, s100
	s_branch .Lp0_e_entry
.Lp0_d_entry:
	v_mov_b32_e32 v2, v220
	s_and_b32 s99, s98, 7
	s_lshr_b32 s100, s98, 3
	s_lshl_b32 s100, s100, 2
	s_add_i32 s0, s100, s99
	s_cmp_lt_u32 s99, 4
	s_mov_b32 s101, 0x2fff
	s_cselect_b32 s101, 0x49ff, s101
	s_cselect_b32 s99, 0x3000, -4
	s_add_i32 s0, s0, s99
	v_lshrrev_b32_e32 v16, 5, v168
	s_movk_i32 s4, 0x84
	v_mov_b32_e32 v4, 0x630
	v_mad_u32_u24 v5, v16, s4, v4
	v_mov_b32_e32 v4, 0xc60
	v_mad_u32_u24 v6, v16, s4, v4
	v_mov_b32_e32 v4, 0x1290
	v_mad_u32_u24 v7, v16, s4, v4
	v_mov_b32_e32 v4, 0x18c0
	v_and_b32_e32 v0, 31, v2
	v_mad_u32_u24 v8, v16, s4, v4
	v_lshlrev_b32_e32 v4, 3, v168
	v_lshl_add_u32 v2, v0, 2, s7
	v_mul_u32_u24_e32 v3, 0x84, v16
	v_lshrrev_b32_e32 v48, 3, v168
	v_and_b32_e32 v4, 56, v4
	s_add_u32 s11, s12, 0x400000
	v_mul_u32_u24_e32 v9, 0x84, v4
	v_lshlrev_b32_e32 v10, 2, v48
	v_add_u32_e32 v57, v2, v3
	v_add_u32_e32 v58, v2, v5
	v_add_u32_e32 v59, v2, v6
	v_add_u32_e32 v60, v2, v7
	v_add_u32_e32 v61, v2, v8
	s_addc_u32 s30, s13, 0
	v_mov_b32_e32 v1, 0
	v_or_b32_e32 v17, 2, v16
	v_or_b32_e32 v18, 4, v16
	v_or_b32_e32 v19, 6, v16
	v_or_b32_e32 v20, 8, v16
	v_or_b32_e32 v21, 10, v16
	v_or_b32_e32 v22, 12, v16
	v_or_b32_e32 v23, 14, v16
	v_or_b32_e32 v24, 16, v16
	v_or_b32_e32 v25, 18, v16
	v_or_b32_e32 v26, 20, v16
	v_or_b32_e32 v27, 22, v16
	v_or_b32_e32 v28, 24, v16
	v_or_b32_e32 v29, 26, v16
	v_or_b32_e32 v30, 28, v16
	v_or_b32_e32 v31, 30, v16
	v_or_b32_e32 v32, 32, v16
	v_or_b32_e32 v33, 34, v16
	v_or_b32_e32 v34, 36, v16
	v_or_b32_e32 v35, 38, v16
	v_or_b32_e32 v36, 40, v16
	v_or_b32_e32 v37, 42, v16
	v_or_b32_e32 v38, 44, v16
	v_or_b32_e32 v39, 46, v16
	v_or_b32_e32 v40, 48, v16
	v_or_b32_e32 v41, 50, v16
	v_or_b32_e32 v42, 52, v16
	v_or_b32_e32 v43, 54, v16
	v_or_b32_e32 v44, 56, v16
	v_or_b32_e32 v45, 58, v16
	v_or_b32_e32 v46, 60, v16
	v_or_b32_e32 v47, 62, v16
	v_add3_u32 v49, s7, v9, v10
	v_or_b32_e32 v50, 8, v48
	v_or_b32_e32 v51, 16, v48
	v_or_b32_e32 v52, 24, v48
	v_or_b32_e32 v53, 0x500, v48
	v_or_b32_e32 v54, 0x508, v48
	v_or_b32_e32 v55, 0x510, v48
	v_or_b32_e32 v56, 0x518, v48
	s_lshl_b32 s31, s0, 5
	s_mov_b32 s34, 0x8000
	s_lshl_b32 s35, s0, 1
	s_movk_i32 s36, 0x800
	s_movk_i32 s37, 0xaff
	s_add_i32 s38, 0, 0x20070
	s_add_i32 s39, 0, 0x20074
	s_mov_b64 s[8:9], 0x200000
	s_mov_b64 s[14:15], 0x2400400
	s_add_i32 s40, 0, 0x20068
	s_add_i32 s41, 0, 0x2006c
	s_mov_b64 s[18:19], 0x2100000
	s_mov_b32 s42, 0x7ffffe00
	s_add_i32 s43, 0, 0x20060
	s_add_i32 s44, 0, 0x20064
	s_mov_b64 s[20:21], 0x1b80000
	s_add_i32 s45, 0, 0x20050
	s_add_i32 s46, 0, 0x20054
	s_mov_b64 s[22:23], 0xb00000
	s_add_i32 s47, 0, 0x20058
	s_add_i32 s48, 0, 0x2005c
	s_mov_b64 s[24:25], 0x1080000
	s_add_i32 s49, 0, 0x20048
	s_add_i32 s50, 0, 0x2004c
	v_lshlrev_b32_e32 v2, 2, v0
	v_add_u32_e32 v62, 0x400, v57
	v_add_u32_e32 v63, 0x400, v58
	v_add_u32_e32 v64, 0x400, v59
	v_add_u32_e32 v65, 0x400, v60
	v_add_u32_e32 v66, 0x400, v61
	v_lshlrev_b32_e32 v0, 1, v4
	v_mov_b32_e32 v67, 0xfffff500
	v_mov_b32_e32 v68, 0x80
	v_mov_b32_e32 v69, 0x67
	v_mov_b32_e32 v70, 0x6f
	v_mov_b32_e32 v71, 0x77
	v_mov_b32_e32 v72, 0x7f
	s_mov_b32 s51, s0
	s_branch .LBB0_43
.LBB0_42:
	s_addk_i32 s51, 0x400
	s_add_i32 s31, s31, s34
	s_add_i32 s35, s35, s36
	s_cmp_gt_i32 s51, s101
	s_cbranch_scc1 .LBB0_112

.Lp0_e_entry:
	s_add_i32 s4, 0, 0x20070
	v_lshlrev_b32_e32 v0, 2, v168
	v_lshl_add_u32 v169, v168, 4, s7
	v_mul_i32_i24_e32 v1, -12, v168
	v_mov_b32_e32 v199, s4
	s_add_i32 s4, 0, 0x20074
	v_mov_b32_e32 v171, 0
	s_mov_b32 s5, 0
	v_mov_b32_e32 v219, s4
	s_add_i32 s11, 0, 0x200a0
	s_add_i32 s30, 0, 0x200a4
	v_lshlrev_b32_e32 v172, 2, v0
	s_movk_i32 s31, 0x1000
	s_movk_i32 s34, 0x2000
	s_mov_b64 s[8:9], 0x100000
	s_add_i32 s35, 0, 0x20078
	s_add_i32 s36, 0, 0x2007c
	s_add_i32 s37, 0, 0x20080
	s_add_i32 s38, 0, 0x20084
	v_lshlrev_b32_e32 v221, 2, v168
	v_add_u32_e32 v222, v169, v1
	s_mov_b64 s[14:15], 0xf000
	s_mov_b32 s39, 0xffff2000
	s_mov_b32 s40, 0xffff4000
	s_mov_b32 s41, 0xffff6000
	s_movk_i32 s42, 0x8000
	s_movk_i32 s43, 0xa000
	s_movk_i32 s44, 0xc000
	s_movk_i32 s45, 0xe000
	s_mov_b64 s[18:19], 0x10000
	s_mov_b64 s[20:21], 0x2800000

.LBB0_110:
	v_add_co_u32_e32 v0, vcc, s39, v176
	v_mov_b32_e32 v173, s24
	s_nop 0
	v_addc_co_u32_e32 v1, vcc, -1, v177, vcc
	global_load_dword v210, v[0:1], off offset:-4096
	global_load_dword v211, v[0:1], off
	v_add_co_u32_e32 v0, vcc, s40, v176
	s_add_i32 s23, s23, 16
	s_nop 0
	v_addc_co_u32_e32 v1, vcc, -1, v177, vcc
	global_load_dword v208, v[0:1], off offset:-4096
	global_load_dword v209, v[0:1], off
	v_add_co_u32_e32 v0, vcc, s41, v176
	s_add_i32 s24, s24, 64
	s_nop 0
	v_addc_co_u32_e32 v1, vcc, -1, v177, vcc
	global_load_dword v206, v[0:1], off offset:-4096
	global_load_dword v207, v[0:1], off
	v_add_co_u32_e32 v0, vcc, s42, v176
	s_cmp_lt_u32 s23, s4
	s_nop 0
	v_addc_co_u32_e32 v1, vcc, -1, v177, vcc
	global_load_dword v204, v[0:1], off offset:-4096
	global_load_dword v205, v[0:1], off
	v_add_co_u32_e32 v0, vcc, s43, v176
	s_waitcnt vmcnt(6)
	v_mov_b32_e32 v44, v211
	v_addc_co_u32_e32 v1, vcc, -1, v177, vcc
	global_load_dword v196, v[0:1], off offset:-4096
	global_load_dword v197, v[0:1], off
	v_add_co_u32_e32 v0, vcc, s44, v176
	v_mov_b32_e32 v218, v211
	s_nop 0
	v_addc_co_u32_e32 v1, vcc, -1, v177, vcc
	global_load_dword v192, v[0:1], off offset:-4096
	global_load_dword v193, v[0:1], off
	v_add_co_u32_e32 v0, vcc, s45, v176
	s_waitcnt vmcnt(6)
	v_mov_b32_e32 v45, v207
	v_addc_co_u32_e32 v1, vcc, -1, v177, vcc
	global_load_dword v200, v[0:1], off offset:-4096
	global_load_dword v198, v[0:1], off
	global_load_dword v194, v[176:177], off offset:-4096
	global_load_dword v170, v[176:177], off
	ds_read_b128 v[160:163], v173
	ds_read_b128 v[156:159], v173 offset:16
	ds_read_b128 v[152:155], v173 offset:32
	ds_read_b128 v[148:151], v173 offset:48
	ds_read_b128 v[164:167], v173 offset:1024
	ds_read_b128 v[124:127], v173 offset:2048
	ds_read_b128 v[128:131], v173 offset:3072
	ds_read_b128 v[100:103], v173 offset:4096
	ds_read_b128 v[104:107], v173 offset:5120
	ds_read_b128 v[76:79], v173 offset:6144
	ds_read_b128 v[80:83], v173 offset:7168
	ds_read_b128 v[52:55], v173 offset:8192
	ds_read_b128 v[56:59], v173 offset:9216
	ds_read_b128 v[28:31], v173 offset:10240
	ds_read_b128 v[32:35], v173 offset:11264
	ds_read_b128 v[0:3], v173 offset:12288
	ds_read_b128 v[4:7], v173 offset:13312
	ds_read_b128 v[8:11], v173 offset:14336
	s_waitcnt lgkmcnt(13)
	v_mov_b32_e32 v237, v164
	v_mov_b32_e32 v164, v161
	v_mov_b32_e32 v236, v160
	v_pk_mul_f32 v[160:161], v[218:219], v[164:165] op_sel_hi:[0,1]
	s_waitcnt lgkmcnt(0)
	v_mul_f32_e32 v12, v211, v9
	v_pk_fma_f32 v[8:9], v[210:211], v[8:9], v[12:13] op_sel_hi:[1,1,0]
	v_pk_fma_f32 v[160:161], v[210:211], v[236:237], v[160:161] op_sel_hi:[0,1,1]
	v_pk_fma_f32 v[8:9], v[208:209], v[10:11], v[8:9]
	v_mul_f32_e32 v10, v209, v11
	v_pk_add_f32 v[202:203], v[10:11], v[8:9] op_sel_hi:[0,1]
	ds_read_b128 v[8:11], v173 offset:15360
	ds_read_b128 v[224:227], v173 offset:1040
	ds_read_b128 v[132:135], v173 offset:2064
	ds_read_b128 v[136:139], v173 offset:3088
	ds_read_b128 v[108:111], v173 offset:4112
	ds_read_b128 v[112:115], v173 offset:5136
	ds_read_b128 v[84:87], v173 offset:6160
	ds_read_b128 v[88:91], v173 offset:7184
	ds_read_b128 v[60:63], v173 offset:8208
	ds_read_b128 v[64:67], v173 offset:9232
	ds_read_b128 v[36:39], v173 offset:10256
	ds_read_b128 v[40:43], v173 offset:11280
	ds_read_b128 v[12:15], v173 offset:12304
	ds_read_b128 v[16:19], v173 offset:13328
	ds_read_b128 v[20:23], v173 offset:14352
	s_waitcnt lgkmcnt(14)
	v_mov_b32_e32 v26, v8
	v_mov_b32_e32 v164, v162
	v_mov_b32_e32 v165, v166
	v_pk_fma_f32 v[160:161], v[208:209], v[164:165], v[160:161] op_sel_hi:[0,1,1]
	s_waitcnt lgkmcnt(0)
	v_mul_f32_e32 v24, v207, v21
	v_pk_fma_f32 v[20:21], v[206:207], v[20:21], v[24:25] op_sel_hi:[1,1,0]
	v_mov_b32_e32 v24, v210
	s_waitcnt vmcnt(8)
	v_pk_fma_f32 v[20:21], v[204:205], v[22:23], v[20:21]
	v_mul_f32_e32 v22, v205, v23
	v_pk_add_f32 v[212:213], v[22:23], v[20:21] op_sel_hi:[0,1]
	ds_read_b128 v[20:23], v173 offset:15376
	v_mov_b32_e32 v25, v206
	v_mov_b32_e32 v162, v209
	v_mov_b32_e32 v166, v163
	v_pk_fma_f32 v[160:161], v[162:163], v[166:167], v[160:161] op_sel_hi:[0,1,1]
	s_waitcnt lgkmcnt(0)
	v_mov_b32_e32 v27, v20
	v_mov_b32_e32 v20, v9
	v_pk_mul_f32 v[8:9], v[44:45], v[20:21]
	v_mov_b32_e32 v20, v208
	v_pk_fma_f32 v[8:9], v[24:25], v[26:27], v[8:9]
	v_mov_b32_e32 v21, v204
	v_mov_b32_e32 v24, v10
	v_mov_b32_e32 v25, v22
	v_pk_fma_f32 v[8:9], v[20:21], v[24:25], v[8:9]
	v_mov_b32_e32 v20, v209
	v_mov_b32_e32 v21, v205
	v_mov_b32_e32 v22, v11
	v_pk_fma_f32 v[214:215], v[20:21], v[22:23], v[8:9]
	ds_read_b128 v[228:231], v173 offset:1056
	ds_read_b128 v[140:143], v173 offset:2080
	ds_read_b128 v[144:147], v173 offset:3104
	ds_read_b128 v[116:119], v173 offset:4128
	ds_read_b128 v[120:123], v173 offset:5152
	ds_read_b128 v[92:95], v173 offset:6176
	ds_read_b128 v[96:99], v173 offset:7200
	ds_read_b128 v[68:71], v173 offset:8224
	ds_read_b128 v[72:75], v173 offset:9248
	ds_read_b128 v[44:47], v173 offset:10272
	ds_read_b128 v[48:51], v173 offset:11296
	ds_read_b128 v[20:23], v173 offset:12320
	ds_read_b128 v[24:27], v173 offset:13344
	ds_read_b128 v[8:11], v173 offset:14368
	v_pk_add_f32 v[164:165], v[188:189], v[160:161]
	v_mov_b32_e32 v167, v224
	v_mov_b32_e32 v160, v207
	v_mov_b32_e32 v224, v157
	v_mov_b32_e32 v166, v156
	v_pk_mul_f32 v[156:157], v[160:161], v[224:225] op_sel_hi:[0,1]
	v_pk_fma_f32 v[156:157], v[206:207], v[166:167], v[156:157] op_sel_hi:[0,1,1]
	v_mov_b32_e32 v166, v158
	v_mov_b32_e32 v167, v226
	v_pk_fma_f32 v[156:157], v[204:205], v[166:167], v[156:157] op_sel_hi:[0,1,1]
	v_mov_b32_e32 v158, v205
	v_mov_b32_e32 v226, v159
	v_pk_fma_f32 v[156:157], v[158:159], v[226:227], v[156:157] op_sel_hi:[0,1,1]
	v_pk_add_f32 v[164:165], v[164:165], v[156:157]
	s_waitcnt lgkmcnt(13)
	v_mov_b32_e32 v167, v228
	v_mov_b32_e32 v228, v153
	v_mov_b32_e32 v166, v152
	v_mov_b32_e32 v203, v214
	v_mov_b32_e32 v213, v215
	v_lshl_add_u64 v[176:177], v[176:177], 0, s[18:19]
	s_waitcnt vmcnt(6) lgkmcnt(0)
	v_mul_f32_e32 v216, v197, v9
	v_pk_fma_f32 v[8:9], v[196:197], v[8:9], v[216:217] op_sel_hi:[1,1,0]
	v_mov_b32_e32 v156, v197
	v_pk_mul_f32 v[152:153], v[156:157], v[228:229] op_sel_hi:[0,1]
	v_pk_fma_f32 v[152:153], v[196:197], v[166:167], v[152:153] op_sel_hi:[0,1,1]
	v_mov_b32_e32 v166, v154
	s_waitcnt vmcnt(4)
	v_pk_fma_f32 v[8:9], v[192:193], v[10:11], v[8:9]
	v_mul_f32_e32 v10, v193, v11
	v_pk_add_f32 v[216:217], v[10:11], v[8:9] op_sel_hi:[0,1]
	ds_read_b128 v[8:11], v173 offset:15392
	ds_read_b128 v[232:235], v173 offset:1072
	v_mov_b32_e32 v167, v230
	v_pk_fma_f32 v[166:167], v[192:193], v[166:167], v[152:153] op_sel_hi:[0,1,1]
	v_mov_b32_e32 v152, v193
	v_mov_b32_e32 v230, v155
	v_pk_fma_f32 v[154:155], v[152:153], v[230:231], v[166:167] op_sel_hi:[0,1,1]
	v_pk_add_f32 v[154:155], v[164:165], v[154:155]
	s_waitcnt lgkmcnt(0)
	v_mov_b32_e32 v165, v232
	v_mov_b32_e32 v232, v149
	v_mov_b32_e32 v164, v148
	s_waitcnt vmcnt(2)
	v_pk_mul_f32 v[148:149], v[198:199], v[232:233] op_sel_hi:[0,1]
	v_pk_fma_f32 v[148:149], v[200:201], v[164:165], v[148:149] op_sel_hi:[0,1,1]
	v_mov_b32_e32 v164, v150
	v_mov_b32_e32 v165, v234
	s_waitcnt vmcnt(1)
	v_pk_fma_f32 v[148:149], v[194:195], v[164:165], v[148:149] op_sel_hi:[0,1,1]
	v_mov_b32_e32 v234, v151
	s_waitcnt vmcnt(0)
	v_pk_fma_f32 v[148:149], v[170:171], v[234:235], v[148:149] op_sel_hi:[0,1,1]
	v_pk_add_f32 v[188:189], v[154:155], v[148:149]
	v_mov_b32_e32 v155, v128
	v_mov_b32_e32 v128, v125
	v_mov_b32_e32 v154, v124
	v_pk_mul_f32 v[124:125], v[218:219], v[128:129] op_sel_hi:[0,1]
	v_pk_fma_f32 v[124:125], v[210:211], v[154:155], v[124:125] op_sel_hi:[0,1,1]
	v_mov_b32_e32 v128, v126
	v_mov_b32_e32 v129, v130
	v_mov_b32_e32 v130, v127
	v_mov_b32_e32 v127, v136
	v_mov_b32_e32 v136, v133
	v_pk_fma_f32 v[124:125], v[208:209], v[128:129], v[124:125] op_sel_hi:[0,1,1]
	v_mov_b32_e32 v126, v132
	v_pk_mul_f32 v[128:129], v[160:161], v[136:137] op_sel_hi:[0,1]
	v_pk_fma_f32 v[126:127], v[206:207], v[126:127], v[128:129] op_sel_hi:[0,1,1]
	v_mov_b32_e32 v128, v134
	v_mov_b32_e32 v129, v138
	v_pk_fma_f32 v[124:125], v[162:163], v[130:131], v[124:125] op_sel_hi:[0,1,1]
	v_pk_fma_f32 v[126:127], v[204:205], v[128:129], v[126:127] op_sel_hi:[0,1,1]
	v_mov_b32_e32 v138, v135
	v_pk_add_f32 v[124:125], v[182:183], v[124:125]
	v_pk_fma_f32 v[126:127], v[158:159], v[138:139], v[126:127] op_sel_hi:[0,1,1]
	ds_read_b128 v[148:151], v173 offset:2096
	ds_read_b128 v[164:167], v173 offset:3120
	v_pk_add_f32 v[124:125], v[124:125], v[126:127]
	v_mov_b32_e32 v127, v144
	v_mov_b32_e32 v144, v141
	v_mov_b32_e32 v126, v140
	v_pk_mul_f32 v[128:129], v[156:157], v[144:145] op_sel_hi:[0,1]
	v_pk_fma_f32 v[126:127], v[196:197], v[126:127], v[128:129] op_sel_hi:[0,1,1]
	v_mov_b32_e32 v128, v142
	v_mov_b32_e32 v129, v146
	v_pk_fma_f32 v[126:127], v[192:193], v[128:129], v[126:127] op_sel_hi:[0,1,1]
	v_mov_b32_e32 v146, v143
	v_mov_b32_e32 v133, v104
	v_mov_b32_e32 v104, v101
	v_pk_fma_f32 v[126:127], v[152:153], v[146:147], v[126:127] op_sel_hi:[0,1,1]
	v_mov_b32_e32 v132, v100
	v_pk_mul_f32 v[100:101], v[218:219], v[104:105] op_sel_hi:[0,1]
	v_pk_add_f32 v[124:125], v[124:125], v[126:127]
	s_waitcnt lgkmcnt(0)
	v_mov_b32_e32 v127, v164
	v_mov_b32_e32 v164, v149
	v_pk_fma_f32 v[100:101], v[210:211], v[132:133], v[100:101] op_sel_hi:[0,1,1]
	v_mov_b32_e32 v104, v102
	v_mov_b32_e32 v105, v106
	v_mov_b32_e32 v106, v103
	v_mov_b32_e32 v103, v112
	v_mov_b32_e32 v112, v109
	v_mov_b32_e32 v126, v148
	v_pk_mul_f32 v[128:129], v[198:199], v[164:165] op_sel_hi:[0,1]
	v_pk_fma_f32 v[100:101], v[208:209], v[104:105], v[100:101] op_sel_hi:[0,1,1]
	v_mov_b32_e32 v102, v108
	v_pk_mul_f32 v[104:105], v[160:161], v[112:113] op_sel_hi:[0,1]
	v_pk_fma_f32 v[126:127], v[200:201], v[126:127], v[128:129] op_sel_hi:[0,1,1]
	v_mov_b32_e32 v128, v150
	v_mov_b32_e32 v129, v166
	v_pk_fma_f32 v[102:103], v[206:207], v[102:103], v[104:105] op_sel_hi:[0,1,1]
	v_mov_b32_e32 v104, v110
	v_mov_b32_e32 v105, v114
	v_pk_fma_f32 v[126:127], v[194:195], v[128:129], v[126:127] op_sel_hi:[0,1,1]
	v_mov_b32_e32 v166, v151
	v_pk_fma_f32 v[100:101], v[162:163], v[106:107], v[100:101] op_sel_hi:[0,1,1]
	v_pk_fma_f32 v[102:103], v[204:205], v[104:105], v[102:103] op_sel_hi:[0,1,1]
	v_mov_b32_e32 v114, v111
	v_pk_fma_f32 v[126:127], v[170:171], v[166:167], v[126:127] op_sel_hi:[0,1,1]
	v_pk_add_f32 v[100:101], v[184:185], v[100:101]
	v_pk_fma_f32 v[102:103], v[158:159], v[114:115], v[102:103] op_sel_hi:[0,1,1]
	v_pk_add_f32 v[182:183], v[124:125], v[126:127]
	ds_read_b128 v[124:127], v173 offset:4144
	ds_read_b128 v[128:131], v173 offset:5168
	v_pk_add_f32 v[100:101], v[100:101], v[102:103]
	v_mov_b32_e32 v103, v120
	v_mov_b32_e32 v120, v117
	v_mov_b32_e32 v102, v116
	v_pk_mul_f32 v[104:105], v[156:157], v[120:121] op_sel_hi:[0,1]
	v_pk_fma_f32 v[102:103], v[196:197], v[102:103], v[104:105] op_sel_hi:[0,1,1]
	v_mov_b32_e32 v104, v118
	v_mov_b32_e32 v105, v122
	v_pk_fma_f32 v[102:103], v[192:193], v[104:105], v[102:103] op_sel_hi:[0,1,1]
	v_mov_b32_e32 v122, v119
	v_mov_b32_e32 v109, v80
	v_mov_b32_e32 v80, v77
	v_pk_fma_f32 v[102:103], v[152:153], v[122:123], v[102:103] op_sel_hi:[0,1,1]
	v_mov_b32_e32 v108, v76
	v_pk_mul_f32 v[76:77], v[218:219], v[80:81] op_sel_hi:[0,1]
	v_pk_add_f32 v[100:101], v[100:101], v[102:103]
	s_waitcnt lgkmcnt(0)
	v_mov_b32_e32 v103, v128
	v_mov_b32_e32 v128, v125
	v_pk_fma_f32 v[76:77], v[210:211], v[108:109], v[76:77] op_sel_hi:[0,1,1]
	v_mov_b32_e32 v80, v78
	v_mov_b32_e32 v81, v82
	v_mov_b32_e32 v82, v79
	v_mov_b32_e32 v79, v88
	v_mov_b32_e32 v88, v85
	v_mov_b32_e32 v102, v124
	v_pk_mul_f32 v[104:105], v[198:199], v[128:129] op_sel_hi:[0,1]
	v_pk_fma_f32 v[76:77], v[208:209], v[80:81], v[76:77] op_sel_hi:[0,1,1]
	v_mov_b32_e32 v78, v84
	v_pk_mul_f32 v[80:81], v[160:161], v[88:89] op_sel_hi:[0,1]
	v_pk_fma_f32 v[102:103], v[200:201], v[102:103], v[104:105] op_sel_hi:[0,1,1]
	v_mov_b32_e32 v104, v126
	v_mov_b32_e32 v105, v130
	v_pk_fma_f32 v[78:79], v[206:207], v[78:79], v[80:81] op_sel_hi:[0,1,1]
	v_mov_b32_e32 v80, v86
	v_mov_b32_e32 v81, v90
	v_pk_fma_f32 v[102:103], v[194:195], v[104:105], v[102:103] op_sel_hi:[0,1,1]
	v_mov_b32_e32 v130, v127
	v_pk_fma_f32 v[76:77], v[162:163], v[82:83], v[76:77] op_sel_hi:[0,1,1]
	v_pk_fma_f32 v[78:79], v[204:205], v[80:81], v[78:79] op_sel_hi:[0,1,1]
	v_mov_b32_e32 v90, v87
	v_pk_fma_f32 v[102:103], v[170:171], v[130:131], v[102:103] op_sel_hi:[0,1,1]
	v_pk_add_f32 v[76:77], v[186:187], v[76:77]
	v_pk_fma_f32 v[78:79], v[158:159], v[90:91], v[78:79] op_sel_hi:[0,1,1]
	v_pk_add_f32 v[184:185], v[100:101], v[102:103]
	ds_read_b128 v[100:103], v173 offset:6192
	ds_read_b128 v[104:107], v173 offset:7216
	v_pk_add_f32 v[76:77], v[76:77], v[78:79]
	v_mov_b32_e32 v79, v96
	v_mov_b32_e32 v96, v93
	v_mov_b32_e32 v78, v92
	v_pk_mul_f32 v[80:81], v[156:157], v[96:97] op_sel_hi:[0,1]
	v_pk_fma_f32 v[78:79], v[196:197], v[78:79], v[80:81] op_sel_hi:[0,1,1]
	v_mov_b32_e32 v80, v94
	v_mov_b32_e32 v81, v98
	v_pk_fma_f32 v[78:79], v[192:193], v[80:81], v[78:79] op_sel_hi:[0,1,1]
	v_mov_b32_e32 v98, v95
	v_mov_b32_e32 v85, v56
	v_mov_b32_e32 v56, v53
	v_pk_fma_f32 v[78:79], v[152:153], v[98:99], v[78:79] op_sel_hi:[0,1,1]
	v_mov_b32_e32 v84, v52
	v_pk_mul_f32 v[52:53], v[218:219], v[56:57] op_sel_hi:[0,1]
	v_pk_add_f32 v[76:77], v[76:77], v[78:79]
	s_waitcnt lgkmcnt(0)
	v_mov_b32_e32 v79, v104
	v_mov_b32_e32 v104, v101
	v_pk_fma_f32 v[52:53], v[210:211], v[84:85], v[52:53] op_sel_hi:[0,1,1]
	v_mov_b32_e32 v56, v54
	v_mov_b32_e32 v57, v58
	v_mov_b32_e32 v58, v55
	v_mov_b32_e32 v55, v64
	v_mov_b32_e32 v64, v61
	v_mov_b32_e32 v78, v100
	v_pk_mul_f32 v[80:81], v[198:199], v[104:105] op_sel_hi:[0,1]
	v_pk_fma_f32 v[52:53], v[208:209], v[56:57], v[52:53] op_sel_hi:[0,1,1]
	v_mov_b32_e32 v54, v60
	v_pk_mul_f32 v[56:57], v[160:161], v[64:65] op_sel_hi:[0,1]
	v_pk_fma_f32 v[78:79], v[200:201], v[78:79], v[80:81] op_sel_hi:[0,1,1]
	v_mov_b32_e32 v80, v102
	v_mov_b32_e32 v81, v106
	v_pk_fma_f32 v[54:55], v[206:207], v[54:55], v[56:57] op_sel_hi:[0,1,1]
	v_mov_b32_e32 v56, v62
	v_mov_b32_e32 v57, v66
	v_pk_fma_f32 v[78:79], v[194:195], v[80:81], v[78:79] op_sel_hi:[0,1,1]
	v_mov_b32_e32 v106, v103
	v_pk_fma_f32 v[52:53], v[162:163], v[58:59], v[52:53] op_sel_hi:[0,1,1]
	v_pk_fma_f32 v[54:55], v[204:205], v[56:57], v[54:55] op_sel_hi:[0,1,1]
	v_mov_b32_e32 v66, v63
	v_pk_fma_f32 v[78:79], v[170:171], v[106:107], v[78:79] op_sel_hi:[0,1,1]
	v_pk_add_f32 v[52:53], v[178:179], v[52:53]
	v_pk_fma_f32 v[54:55], v[158:159], v[66:67], v[54:55] op_sel_hi:[0,1,1]
	v_pk_add_f32 v[186:187], v[76:77], v[78:79]
	ds_read_b128 v[76:79], v173 offset:8240
	ds_read_b128 v[80:83], v173 offset:9264
	v_pk_add_f32 v[52:53], v[52:53], v[54:55]
	v_mov_b32_e32 v55, v72
	v_mov_b32_e32 v72, v69
	v_mov_b32_e32 v54, v68
	v_pk_mul_f32 v[56:57], v[156:157], v[72:73] op_sel_hi:[0,1]
	v_pk_fma_f32 v[54:55], v[196:197], v[54:55], v[56:57] op_sel_hi:[0,1,1]
	v_mov_b32_e32 v56, v70
	v_mov_b32_e32 v57, v74
	v_pk_fma_f32 v[54:55], v[192:193], v[56:57], v[54:55] op_sel_hi:[0,1,1]
	v_mov_b32_e32 v74, v71
	v_mov_b32_e32 v61, v32
	v_mov_b32_e32 v32, v29
	v_pk_fma_f32 v[54:55], v[152:153], v[74:75], v[54:55] op_sel_hi:[0,1,1]
	v_mov_b32_e32 v60, v28
	v_pk_mul_f32 v[28:29], v[218:219], v[32:33] op_sel_hi:[0,1]
	v_pk_add_f32 v[52:53], v[52:53], v[54:55]
	s_waitcnt lgkmcnt(0)
	v_mov_b32_e32 v55, v80
	v_mov_b32_e32 v80, v77
	v_pk_fma_f32 v[28:29], v[210:211], v[60:61], v[28:29] op_sel_hi:[0,1,1]
	v_mov_b32_e32 v32, v30
	v_mov_b32_e32 v33, v34
	v_mov_b32_e32 v34, v31
	v_mov_b32_e32 v31, v40
	v_mov_b32_e32 v40, v37
	v_mov_b32_e32 v54, v76
	v_pk_mul_f32 v[56:57], v[198:199], v[80:81] op_sel_hi:[0,1]
	v_pk_fma_f32 v[28:29], v[208:209], v[32:33], v[28:29] op_sel_hi:[0,1,1]
	v_mov_b32_e32 v30, v36
	v_pk_mul_f32 v[32:33], v[160:161], v[40:41] op_sel_hi:[0,1]
	v_pk_fma_f32 v[54:55], v[200:201], v[54:55], v[56:57] op_sel_hi:[0,1,1]
	v_mov_b32_e32 v56, v78
	v_mov_b32_e32 v57, v82
	v_pk_fma_f32 v[30:31], v[206:207], v[30:31], v[32:33] op_sel_hi:[0,1,1]
	v_mov_b32_e32 v32, v38
	v_mov_b32_e32 v33, v42
	v_pk_fma_f32 v[54:55], v[194:195], v[56:57], v[54:55] op_sel_hi:[0,1,1]
	v_mov_b32_e32 v82, v79
	v_pk_fma_f32 v[28:29], v[162:163], v[34:35], v[28:29] op_sel_hi:[0,1,1]
	v_pk_fma_f32 v[30:31], v[204:205], v[32:33], v[30:31] op_sel_hi:[0,1,1]
	v_mov_b32_e32 v42, v39
	v_pk_fma_f32 v[54:55], v[170:171], v[82:83], v[54:55] op_sel_hi:[0,1,1]
	v_pk_add_f32 v[28:29], v[180:181], v[28:29]
	v_pk_fma_f32 v[30:31], v[158:159], v[42:43], v[30:31] op_sel_hi:[0,1,1]
	v_pk_add_f32 v[178:179], v[52:53], v[54:55]
	ds_read_b128 v[52:55], v173 offset:10288
	ds_read_b128 v[56:59], v173 offset:11312
	v_pk_add_f32 v[28:29], v[28:29], v[30:31]
	v_mov_b32_e32 v31, v48
	v_mov_b32_e32 v48, v45
	v_mov_b32_e32 v30, v44
	v_pk_mul_f32 v[32:33], v[156:157], v[48:49] op_sel_hi:[0,1]
	v_pk_fma_f32 v[30:31], v[196:197], v[30:31], v[32:33] op_sel_hi:[0,1,1]
	v_mov_b32_e32 v32, v46
	v_mov_b32_e32 v33, v50
	v_pk_fma_f32 v[30:31], v[192:193], v[32:33], v[30:31] op_sel_hi:[0,1,1]
	v_mov_b32_e32 v50, v47
	v_mov_b32_e32 v37, v4
	v_mov_b32_e32 v4, v1
	v_pk_fma_f32 v[30:31], v[152:153], v[50:51], v[30:31] op_sel_hi:[0,1,1]
	v_mov_b32_e32 v36, v0
	v_pk_mul_f32 v[0:1], v[218:219], v[4:5] op_sel_hi:[0,1]
	v_pk_add_f32 v[28:29], v[28:29], v[30:31]
	s_waitcnt lgkmcnt(0)
	v_mov_b32_e32 v31, v56
	v_mov_b32_e32 v56, v53
	v_pk_fma_f32 v[0:1], v[210:211], v[36:37], v[0:1] op_sel_hi:[0,1,1]
	v_mov_b32_e32 v4, v2
	v_mov_b32_e32 v5, v6
	v_mov_b32_e32 v6, v3
	v_mov_b32_e32 v3, v16
	v_mov_b32_e32 v16, v13
	v_mov_b32_e32 v30, v52
	v_pk_mul_f32 v[32:33], v[198:199], v[56:57] op_sel_hi:[0,1]
	v_pk_fma_f32 v[0:1], v[208:209], v[4:5], v[0:1] op_sel_hi:[0,1,1]
	v_mov_b32_e32 v2, v12
	v_pk_mul_f32 v[4:5], v[160:161], v[16:17] op_sel_hi:[0,1]
	v_pk_fma_f32 v[30:31], v[200:201], v[30:31], v[32:33] op_sel_hi:[0,1,1]
	v_mov_b32_e32 v32, v54
	v_mov_b32_e32 v33, v58
	v_pk_fma_f32 v[2:3], v[206:207], v[2:3], v[4:5] op_sel_hi:[0,1,1]
	v_mov_b32_e32 v4, v14
	v_mov_b32_e32 v5, v18
	v_pk_fma_f32 v[30:31], v[194:195], v[32:33], v[30:31] op_sel_hi:[0,1,1]
	v_mov_b32_e32 v58, v55
	v_pk_fma_f32 v[0:1], v[162:163], v[6:7], v[0:1] op_sel_hi:[0,1,1]
	v_pk_fma_f32 v[2:3], v[204:205], v[4:5], v[2:3] op_sel_hi:[0,1,1]
	v_mov_b32_e32 v18, v15
	v_pk_fma_f32 v[30:31], v[170:171], v[58:59], v[30:31] op_sel_hi:[0,1,1]
	v_pk_add_f32 v[0:1], v[190:191], v[0:1]
	v_pk_fma_f32 v[2:3], v[158:159], v[18:19], v[2:3] op_sel_hi:[0,1,1]
	v_pk_add_f32 v[180:181], v[28:29], v[30:31]
	ds_read_b128 v[28:31], v173 offset:12336
	ds_read_b128 v[32:35], v173 offset:13360
	v_pk_add_f32 v[0:1], v[0:1], v[2:3]
	v_mov_b32_e32 v3, v24
	v_mov_b32_e32 v24, v21
	v_mov_b32_e32 v2, v20
	v_pk_mul_f32 v[4:5], v[156:157], v[24:25] op_sel_hi:[0,1]
	v_pk_fma_f32 v[2:3], v[196:197], v[2:3], v[4:5] op_sel_hi:[0,1,1]
	v_mov_b32_e32 v4, v22
	v_mov_b32_e32 v5, v26
	v_pk_fma_f32 v[2:3], v[192:193], v[4:5], v[2:3] op_sel_hi:[0,1,1]
	v_mov_b32_e32 v26, v23
	v_pk_fma_f32 v[2:3], v[152:153], v[26:27], v[2:3] op_sel_hi:[0,1,1]
	v_pk_add_f32 v[0:1], v[0:1], v[2:3]
	s_waitcnt lgkmcnt(0)
	v_mov_b32_e32 v3, v32
	v_mov_b32_e32 v32, v29
	v_mov_b32_e32 v2, v28
	v_pk_mul_f32 v[4:5], v[198:199], v[32:33] op_sel_hi:[0,1]
	v_pk_fma_f32 v[2:3], v[200:201], v[2:3], v[4:5] op_sel_hi:[0,1,1]
	v_mov_b32_e32 v4, v30
	v_mov_b32_e32 v5, v34
	v_pk_fma_f32 v[2:3], v[194:195], v[4:5], v[2:3] op_sel_hi:[0,1,1]
	v_mov_b32_e32 v34, v31
	v_pk_fma_f32 v[2:3], v[170:171], v[34:35], v[2:3] op_sel_hi:[0,1,1]
	v_pk_add_f32 v[190:191], v[0:1], v[2:3]
	ds_read_b128 v[0:3], v173 offset:14384
	v_mov_b32_e32 v201, v198
	v_mov_b32_e32 v195, v170
	v_mov_b32_e32 v14, v197
	v_mov_b32_e32 v15, v198
	s_waitcnt lgkmcnt(0)
	v_mul_f32_e32 v4, v198, v1
	v_pk_fma_f32 v[0:1], v[200:201], v[0:1], v[4:5] op_sel_hi:[1,1,0]
	v_mov_b32_e32 v6, v196
	v_pk_fma_f32 v[0:1], v[194:195], v[2:3], v[0:1]
	v_mul_f32_e32 v2, v170, v3
	v_pk_add_f32 v[4:5], v[2:3], v[0:1] op_sel_hi:[0,1]
	ds_read_b128 v[0:3], v173 offset:15408
	v_mov_b32_e32 v7, v200
	v_mov_b32_e32 v12, v8
	v_mov_b32_e32 v8, v10
	s_waitcnt lgkmcnt(0)
	v_mov_b32_e32 v13, v0
	v_mov_b32_e32 v0, v9
	v_pk_mul_f32 v[0:1], v[14:15], v[0:1]
	v_mov_b32_e32 v9, v2
	v_pk_fma_f32 v[0:1], v[6:7], v[12:13], v[0:1]
	v_mov_b32_e32 v6, v192
	v_mov_b32_e32 v7, v194
	v_pk_fma_f32 v[0:1], v[6:7], v[8:9], v[0:1]
	v_mov_b32_e32 v6, v193
	v_mov_b32_e32 v7, v170
	v_mov_b32_e32 v2, v11
	v_pk_fma_f32 v[0:1], v[6:7], v[2:3], v[0:1]
	v_pk_add_f32 v[2:3], v[174:175], v[202:203]
	v_mov_b32_e32 v217, v0
	v_pk_add_f32 v[2:3], v[2:3], v[212:213]
	v_mov_b32_e32 v5, v1
	v_pk_add_f32 v[2:3], v[2:3], v[216:217]
	s_nop 0
	v_pk_add_f32 v[174:175], v[2:3], v[4:5]
	s_cbranch_scc1 .LBB0_110
	s_mul_hi_i32 s4, s22, 0x2600000
	s_mul_i32 s22, s22, 0x2600000
	s_add_u32 s22, s12, s22
	s_addc_u32 s23, s13, s4
	v_lshlrev_b32_e32 v170, 11, v223
	v_lshl_add_u64 v[0:1], s[22:23], 0, v[170:171]
	s_lshl_b32 s4, s46, 1
	v_lshl_add_u64 v[8:9], v[0:1], 0, s[4:5]
	v_lshl_add_u64 v[10:11], v[8:9], 0, s[20:21]
	v_add_co_u32_e32 v8, vcc, 0x2800000, v8
	v_cvt_pk_bf16_f32 v0, v188, v189
	v_cvt_pk_bf16_f32 v1, v182, v183
	v_cvt_pk_bf16_f32 v2, v184, v185
	v_cvt_pk_bf16_f32 v3, v186, v187
	v_addc_co_u32_e32 v9, vcc, 0, v9, vcc
	v_cvt_pk_bf16_f32 v4, v178, v179
	v_cvt_pk_bf16_f32 v5, v180, v181
	v_cvt_pk_bf16_f32 v6, v190, v191
	v_cvt_pk_bf16_f32 v7, v174, v175
	global_store_dwordx4 v[8:9], v[0:3], off
	global_store_dwordx4 v[10:11], v[4:7], off offset:16
	s_waitcnt lgkmcnt(0)
	s_add_i32 s0, s0, s10
	s_cmpk_lt_i32 s0, 0x400
	s_cbranch_scc1 .LBB0_105
	s_branch .Lp0_d_entry

	.amdhsa_kernel _Z10fwd_kernel6Params
		.amdhsa_group_segment_fixed_size 0
		.amdhsa_private_segment_fixed_size 0
		.amdhsa_kernarg_size 464
		.amdhsa_user_sgpr_count 2
		.amdhsa_user_sgpr_dispatch_ptr 0
		.amdhsa_user_sgpr_queue_ptr 0
		.amdhsa_user_sgpr_kernarg_segment_ptr 1
		.amdhsa_user_sgpr_dispatch_id 0
		.amdhsa_user_sgpr_kernarg_preload_length 0
		.amdhsa_user_sgpr_kernarg_preload_offset 0
		.amdhsa_user_sgpr_private_segment_size 0
		.amdhsa_uses_dynamic_stack 0
		.amdhsa_enable_private_segment 0
		.amdhsa_system_sgpr_workgroup_id_x 1
		.amdhsa_system_sgpr_workgroup_id_y 0
		.amdhsa_system_sgpr_workgroup_id_z 0
		.amdhsa_system_sgpr_workgroup_info 0
		.amdhsa_system_vgpr_workitem_id 2
		.amdhsa_next_free_vgpr 256
		.amdhsa_next_free_sgpr 102
		.amdhsa_accum_offset 256
		.amdhsa_reserve_vcc 1
		.amdhsa_float_round_mode_32 0
		.amdhsa_float_round_mode_16_64 0
		.amdhsa_float_denorm_mode_32 3
		.amdhsa_float_denorm_mode_16_64 3
		.amdhsa_dx10_clamp 1
		.amdhsa_ieee_mode 1
		.amdhsa_fp16_overflow 0
		.amdhsa_tg_split 0
		.amdhsa_exception_fp_ieee_invalid_op 0
		.amdhsa_exception_fp_denorm_src 0
		.amdhsa_exception_fp_ieee_div_zero 0
		.amdhsa_exception_fp_ieee_overflow 0
		.amdhsa_exception_fp_ieee_underflow 0
		.amdhsa_exception_fp_ieee_inexact 0
		.amdhsa_exception_int_div_zero 0
	.end_amdhsa_kernel

amdhsa.kernels:
  - .agpr_count:     0
    .args:
      - .offset:         0
        .size:           208
        .value_kind:     by_value
      - .offset:         208
        .size:           4
        .value_kind:     hidden_block_count_x
      - .offset:         212
        .size:           4
        .value_kind:     hidden_block_count_y
      - .offset:         216
        .size:           4
        .value_kind:     hidden_block_count_z
      - .offset:         220
        .size:           2
        .value_kind:     hidden_group_size_x
      - .offset:         222
        .size:           2
        .value_kind:     hidden_group_size_y
      - .offset:         224
        .size:           2
        .value_kind:     hidden_group_size_z
      - .offset:         226
        .size:           2
        .value_kind:     hidden_remainder_x
      - .offset:         228
        .size:           2
        .value_kind:     hidden_remainder_y
      - .offset:         230
        .size:           2
        .value_kind:     hidden_remainder_z
      - .offset:         248
        .size:           8
        .value_kind:     hidden_global_offset_x
      - .offset:         256
        .size:           8
        .value_kind:     hidden_global_offset_y
      - .offset:         264
        .size:           8
        .value_kind:     hidden_global_offset_z
      - .offset:         272
        .size:           2
        .value_kind:     hidden_grid_dims
      - .offset:         296
        .size:           8
        .value_kind:     hidden_multigrid_sync_arg
      - .offset:         328
        .size:           4
        .value_kind:     hidden_dynamic_lds_size
    .group_segment_fixed_size: 0
    .kernarg_segment_align: 8
    .kernarg_segment_size: 464
    .language:       OpenCL C
    .language_version:
      - 2
      - 0
    .max_flat_workgroup_size: 512
    .name:           _Z10fwd_kernel6Params
    .private_segment_fixed_size: 0
    .sgpr_count:     108
    .sgpr_spill_count: 99
    .symbol:         _Z10fwd_kernel6Params.kd
    .uniform_work_group_size: 1
    .uses_dynamic_stack: false
    .vgpr_count:     256
    .vgpr_spill_count: 0
    .wavefront_size: 64
